# grid barrier: one no-return atomic per workgroup on a monotonic arrival counter in zeroed workspace (was cooperative-groups returning-atomic word); in-proj epilogue sum-of-squares loads batched
# speedup vs baseline: 1.1146x; 1.0425x over previous
; #define LAS __attribute__((address_space(3)))
; __global__ void __launch_bounds__(512, 2) mega_fwd(Args a_byval) {
;     extern __shared__ __attribute__((aligned(16))) unsigned char lds_raw[];
;     cg::grid_group grid = cg::this_grid();
;     const int ph_lo = a_byval.ph_lo, ph_hi = a_byval.ph_hi;
;     const int wave0 = __builtin_amdgcn_readfirstlane((int)threadIdx.x >> 6);
;     const int it_hi = ph_hi + (PROBE_DUP >= 0 ? 1 : 0);
;     for (int it = ph_lo; it < it_hi; ++it) {
;     const int ph = (PROBE_DUP >= 0 && it > PROBE_DUP) ? it - 1 : it;
;     const __attribute__((address_space(4))) unsigned char* kap = (const __attribute__((address_space(4))) unsigned char*)__builtin_amdgcn_kernarg_segment_ptr();
;     asm volatile("" : "+s"(kap));
;     const __attribute__((address_space(4))) Args& a = *(const __attribute__((address_space(4))) Args*)kap;
;     LAS unsigned char* lds = (LAS unsigned char*)lds_raw;
;     const int wave = wave0;
;     int G = gridDim.x, bx = blockIdx.x; asm volatile("" : "+s"(G), "+s"(bx));
;     const int vcu = (G % 8 == 0) ? (bx % 8) * (G / 8) + bx / 8 : bx;
;     const int gw = vcu * 8 + wave, NGW = G * 8;
;     const int gwm = wave * G + vcu;
.LBB0_1:
	s_mov_b32 s101, 0
	s_mov_b32 s62, s2
	s_add_u32 s2, s58, 0xb0
	s_addc_u32 s3, s59, 0
	s_lshr_b32 s50, s0, 6
	v_writelane_b32 v255, s2, 0
	s_lshl_b32 s1, s50, 14
	s_load_dword s48, s[58:59], 0xb0
	v_writelane_b32 v255, s3, 1
	v_writelane_b32 v255, s1, 2
	s_add_i32 s56, s1, 0
	s_and_b32 s1, s0, 0xffffffc0
	s_lshl_b32 s2, s50, 7
	s_cmp_lg_u32 s2, 0x7fffff80
	s_cselect_b64 s[74:75], -1, 0
	s_ashr_i32 s3, s2, 31
	s_cmp_lt_u32 s0, 64
	v_writelane_b32 v255, s1, 3
	s_cselect_b64 s[60:61], -1, 0
	s_cmp_gt_u32 s0, 63
	v_writelane_b32 v255, s2, 4
	s_cselect_b64 s[84:85], -1, 0
	s_waitcnt lgkmcnt(0)
	s_cmpk_eq_i32 s48, 0x100
	v_writelane_b32 v255, s3, 5
	s_cselect_b64 s[0:1], -1, 0
	v_writelane_b32 v255, s0, 6
	v_lshrrev_b32_e32 v2, 20, v0
	v_lshrrev_b32_e32 v0, 10, v0
	v_writelane_b32 v255, s1, 7
	v_or_b32_e32 v0, v0, v2
	s_movk_i32 s0, 0x3ff
	v_and_or_b32 v0, v0, s0, v1
	v_cmp_eq_u32_e64 s[0:1], 0, v0
	s_mov_b32 s53, 0
	s_movk_i32 s57, 0x100
	v_writelane_b32 v255, s0, 8
	v_mov_b32_e32 v252, 0x358637bd
	s_mov_b32 s49, 0x800000
	v_writelane_b32 v255, s1, 9
	s_lshl_b32 s0, s50, 3
	s_or_b32 s0, s0, 4
	v_writelane_b32 v255, s0, 10
	v_writelane_b32 v255, s62, 11
	v_writelane_b32 v255, s58, 12
	s_movk_i32 s86, 0x1000
	v_mov_b32_e32 v129, 0
	v_writelane_b32 v255, s59, 13
	v_writelane_b32 v255, s48, 14
	v_writelane_b32 v255, s50, 15
	v_writelane_b32 v255, s56, 16
	v_writelane_b32 v255, s74, 17
	s_movk_i32 s41, 0x600
	s_movk_i32 s43, 0xff
	v_writelane_b32 v255, s75, 18
	v_writelane_b32 v255, s60, 19
	s_mov_b32 s63, 0x8400
	s_movk_i32 s94, 0xd0
	v_writelane_b32 v255, s61, 20
	v_writelane_b32 v255, s84, 21
	s_mov_b32 s33, 0x41000000
	s_movk_i32 s77, 0x5800
	s_mov_b32 s78, 0x10000
	s_mov_b32 s79, 0x30000
	s_mov_b32 s76, 0x18000
	s_mov_b32 s51, 0x500000
	s_movk_i32 s1, 0x1600
	v_mov_b64_e32 v[238:239], 0x100
	s_mov_b64 s[54:55], 0x80
	v_writelane_b32 v255, s85, 22
	s_branch .LBB0_5

; __device__ __forceinline__ float sum4(f32x4 v) { return (v.x + v.y) + (v.z + v.w); }
; __device__ __forceinline__ float quad_sum(float t, int lane) { t += shx(t, 16, lane); t += shx(t, 32, lane); return t; }
;     template <int A0, int A1> __device__ __forceinline__ void run(const f32x4 (&acc)[2][2][4][2], const Unit& u, int wr, int wc, int fr, int fq) const {
;     ...
; #pragma unroll
;         for (int ai = A0; ai < A1; ++ai)
; #pragma unroll
;             for (int m = 0; m < 4; ++m) {
;                 const int row = row0 + ai * 128 + m * 16;
;                 const float t = quad_sum(sum4(*(const f32x4*)(ssqp + (size_t)row * 16 + 4 * fq)), fq * 16 + fr);
;                 const float rr = rsqrtf(t * (1.0f / 1024.0f) + EPS);
;                 f32x4 v[2][2];
; #pragma unroll
;                 for (int bj = 0; bj < 2; ++bj)
; #pragma unroll
;                     for (int n = 0; n < 2; ++n) v[bj][n] = acc[ai][bj][m][n] * rr + b[bj][n];
.LBB0_796:
	s_lshl_b32 s24, s76, 8
	s_add_i32 s24, s24, s47
	v_or_b32_e32 v162, s24, v170
	v_ashrrev_i32_e32 v163, 31, v162
	v_lshlrev_b64 v[164:165], 6, v[162:163]
	v_lshl_add_u64 v[48:49], v[152:153], 0, v[164:165]
	global_load_dwordx4 v[184:187], v[48:49], off offset:1024
	global_load_dwordx4 v[188:191], v[48:49], off offset:2048
	global_load_dwordx4 v[192:195], v[48:49], off offset:3072
	v_mov_b32_e32 v212, 0x2000
	v_mov_b32_e32 v213, 0
	v_lshl_add_u64 v[212:213], v[48:49], 0, v[212:213]
	global_load_dwordx4 v[196:199], v[212:213], off offset:0
	global_load_dwordx4 v[200:203], v[212:213], off offset:1024
	global_load_dwordx4 v[204:207], v[212:213], off offset:2048
	global_load_dwordx4 v[208:211], v[212:213], off offset:3072
	global_load_dwordx4 v[48:51], v[48:49], off
	s_cmp_lt_u32 s76, 64
	s_cselect_b32 s10, s0, 0x1000
	s_cmp_gt_i32 s76, 31
	s_cselect_b32 s10, s10, 0
	s_lshl_b32 s10, s10, 2
	v_lshl_or_b32 v160, s80, 8, v178
	s_add_u32 s10, s44, s10
	s_addc_u32 s11, s45, 0
	v_ashrrev_i32_e32 v161, 31, v160
	s_cmp_lt_i32 s80, 1
	s_waitcnt vmcnt(0)
	v_mov_b32_e32 v52, v49
	v_mov_b32_e32 v53, v50
	v_mov_b32_e32 v49, v51
	v_pk_add_f32 v[48:49], v[52:53], v[48:49]
	v_lshl_add_u64 v[52:53], v[160:161], 2, s[10:11]
	v_add_f32_e32 v48, v48, v49
	ds_bpermute_b32 v49, v172, v48
	s_waitcnt lgkmcnt(0)
	v_add_f32_e32 v166, v48, v49
	global_load_dwordx4 v[68:71], v[52:53], off
	global_load_dwordx4 v[64:67], v[52:53], off offset:16
	global_load_dwordx4 v[48:51], v[52:53], off offset:528
	s_nop 0
	global_load_dwordx4 v[52:55], v[52:53], off offset:512
	ds_bpermute_b32 v167, v173, v166
	s_waitcnt lgkmcnt(0)
	v_add_f32_e32 v166, v166, v167
	v_fmamk_f32 v166, v166, 0x3a800000, v252
	v_mul_f32_e32 v167, 0x4b800000, v166
	v_cmp_gt_f32_e32 vcc, s49, v166
	s_nop 1
	v_cndmask_b32_e32 v166, v166, v167, vcc
	v_rsq_f32_e32 v166, v166
	s_nop 0
	v_mul_f32_e32 v167, 0x45800000, v166
	v_cndmask_b32_e32 v168, v166, v167, vcc
	s_waitcnt vmcnt(3)
	v_pk_fma_f32 v[144:145], v[144:145], v[168:169], v[70:71] op_sel_hi:[1,0,1]
	v_pk_fma_f32 v[142:143], v[142:143], v[168:169], v[68:69] op_sel_hi:[1,0,1]
	s_waitcnt vmcnt(2)
	v_pk_fma_f32 v[140:141], v[140:141], v[168:169], v[66:67] op_sel_hi:[1,0,1]
	v_pk_fma_f32 v[138:139], v[138:139], v[168:169], v[64:65] op_sel_hi:[1,0,1]
	s_cbranch_scc1 .LBB0_799
	s_mov_b64 s[20:21], 0
	s_cmp_eq_u32 s80, 1
	s_mov_b64 s[10:11], 0
	s_cbranch_scc0 .LBB0_800
	v_mov_b32_e32 v180, v143
	v_mov_b32_e32 v181, v139
	v_mov_b32_e32 v166, v142
	v_mov_b32_e32 v167, v138
	v_pk_mul_f32 v[180:181], v[180:181], v[180:181]
	v_mov_b32_e32 v182, v145
	v_mov_b32_e32 v183, v141
	v_pk_fma_f32 v[166:167], v[166:167], v[166:167], v[180:181]
	v_mov_b32_e32 v180, v144
	v_mov_b32_e32 v181, v140
	v_pk_mul_f32 v[182:183], v[182:183], v[182:183]
	s_and_b64 s[10:11], s[4:5], exec
	v_pk_fma_f32 v[180:181], v[180:181], v[180:181], v[182:183]
	s_nop 0
	v_pk_add_f32 v[166:167], v[166:167], v[180:181]
	s_nop 0
	v_add_f32_e32 v166, v166, v167
	ds_bpermute_b32 v167, v172, v166
	s_waitcnt lgkmcnt(0)
	v_add_f32_e32 v180, v166, v167
	ds_bpermute_b32 v181, v173, v180
	s_branch .LBB0_800

; __device__ __forceinline__ float sum4(f32x4 v) { return (v.x + v.y) + (v.z + v.w); }
; __device__ __forceinline__ float quad_sum(float t, int lane) { t += shx(t, 16, lane); t += shx(t, 32, lane); return t; }
;     template <int A0, int A1> __device__ __forceinline__ void run(const f32x4 (&acc)[2][2][4][2], const Unit& u, int wr, int wc, int fr, int fq) const {
;     ...
;             for (int m = 0; m < 4; ++m) {
;                 const int row = row0 + ai * 128 + m * 16;
;                 const float t = quad_sum(sum4(*(const f32x4*)(ssqp + (size_t)row * 16 + 4 * fq)), fq * 16 + fr);
;                 const float rr = rsqrtf(t * (1.0f / 1024.0f) + EPS);
;                 f32x4 v[2][2];
; #pragma unroll
;                 for (int bj = 0; bj < 2; ++bj)
; #pragma unroll
;                     for (int n = 0; n < 2; ++n) v[bj][n] = acc[ai][bj][m][n] * rr + b[bj][n];
.LBB0_811:
	s_nop 1
	v_or_b32_e32 v132, 16, v162
	v_ashrrev_i32_e32 v133, 31, v132
	v_lshlrev_b64 v[130:131], 6, v[132:133]
	v_lshl_add_u64 v[134:135], v[152:153], 0, v[130:131]
	s_nop 1
	v_mov_b64_e32 v[134:135], v[184:185]
	v_mov_b64_e32 v[136:137], v[186:187]
	s_cmp_lt_i32 s80, 1
	s_waitcnt vmcnt(0)
	v_mov_b32_e32 v138, v135
	v_mov_b32_e32 v139, v136
	v_mov_b32_e32 v135, v137
	v_pk_add_f32 v[134:135], v[138:139], v[134:135]
	s_nop 0
	v_add_f32_e32 v134, v134, v135
	ds_bpermute_b32 v135, v172, v134
	s_waitcnt lgkmcnt(0)
	v_add_f32_e32 v134, v134, v135
	ds_bpermute_b32 v135, v173, v134
	s_waitcnt lgkmcnt(0)
	v_add_f32_e32 v134, v134, v135
	v_fmamk_f32 v134, v134, 0x3a800000, v252
	v_mul_f32_e32 v135, 0x4b800000, v134
	v_cmp_gt_f32_e32 vcc, s49, v134
	s_nop 1
	v_cndmask_b32_e32 v134, v134, v135, vcc
	v_rsq_f32_e32 v134, v134
	s_nop 0
	v_mul_f32_e32 v135, 0x45800000, v134
	v_cndmask_b32_e32 v136, v134, v135, vcc
	v_pk_fma_f32 v[126:127], v[126:127], v[136:137], v[70:71] op_sel_hi:[1,0,1]
	v_pk_fma_f32 v[124:125], v[124:125], v[136:137], v[68:69] op_sel_hi:[1,0,1]
	v_pk_fma_f32 v[122:123], v[122:123], v[136:137], v[66:67] op_sel_hi:[1,0,1]
	v_pk_fma_f32 v[120:121], v[120:121], v[136:137], v[64:65] op_sel_hi:[1,0,1]
	s_cbranch_scc1 .LBB0_814
	s_mov_b64 s[34:35], 0
	s_cmp_eq_u32 s80, 1
	s_mov_b64 s[20:21], 0
	s_cbranch_scc0 .LBB0_815
	v_mov_b32_e32 v138, v125
	v_mov_b32_e32 v139, v121
	v_mov_b32_e32 v134, v124
	v_mov_b32_e32 v135, v120
	v_pk_mul_f32 v[138:139], v[138:139], v[138:139]
	v_mov_b32_e32 v140, v127
	v_mov_b32_e32 v141, v123
	v_pk_fma_f32 v[134:135], v[134:135], v[134:135], v[138:139]
	v_mov_b32_e32 v138, v126
	v_mov_b32_e32 v139, v122
	v_pk_mul_f32 v[140:141], v[140:141], v[140:141]
	s_and_b64 s[20:21], s[4:5], exec
	v_pk_fma_f32 v[138:139], v[138:139], v[138:139], v[140:141]
	s_nop 0
	v_pk_add_f32 v[134:135], v[134:135], v[138:139]
	s_nop 0
	v_add_f32_e32 v134, v134, v135
	ds_bpermute_b32 v135, v172, v134
	s_waitcnt lgkmcnt(0)
	v_add_f32_e32 v138, v134, v135
	ds_bpermute_b32 v139, v173, v138
	s_branch .LBB0_815

; __device__ __forceinline__ float sum4(f32x4 v) { return (v.x + v.y) + (v.z + v.w); }
; __device__ __forceinline__ float quad_sum(float t, int lane) { t += shx(t, 16, lane); t += shx(t, 32, lane); return t; }
;     template <int A0, int A1> __device__ __forceinline__ void run(const f32x4 (&acc)[2][2][4][2], const Unit& u, int wr, int wc, int fr, int fq) const {
;     ...
;             for (int m = 0; m < 4; ++m) {
;                 const int row = row0 + ai * 128 + m * 16;
;                 const float t = quad_sum(sum4(*(const f32x4*)(ssqp + (size_t)row * 16 + 4 * fq)), fq * 16 + fr);
;                 const float rr = rsqrtf(t * (1.0f / 1024.0f) + EPS);
;                 f32x4 v[2][2];
; #pragma unroll
;                 for (int bj = 0; bj < 2; ++bj)
; #pragma unroll
;                     for (int n = 0; n < 2; ++n) v[bj][n] = acc[ai][bj][m][n] * rr + b[bj][n];
.LBB0_826:
	s_nop 1
	v_or_b32_e32 v114, 32, v162
	v_ashrrev_i32_e32 v115, 31, v114
	v_lshlrev_b64 v[112:113], 6, v[114:115]
	v_lshl_add_u64 v[116:117], v[152:153], 0, v[112:113]
	s_nop 1
	v_mov_b64_e32 v[116:117], v[188:189]
	v_mov_b64_e32 v[118:119], v[190:191]
	s_cmp_lt_i32 s80, 1
	s_waitcnt vmcnt(0)
	v_mov_b32_e32 v120, v117
	v_mov_b32_e32 v121, v118
	v_mov_b32_e32 v117, v119
	v_pk_add_f32 v[116:117], v[120:121], v[116:117]
	s_nop 0
	v_add_f32_e32 v116, v116, v117
	ds_bpermute_b32 v117, v172, v116
	s_waitcnt lgkmcnt(0)
	v_add_f32_e32 v116, v116, v117
	ds_bpermute_b32 v117, v173, v116
	s_waitcnt lgkmcnt(0)
	v_add_f32_e32 v116, v116, v117
	v_fmamk_f32 v116, v116, 0x3a800000, v252
	v_mul_f32_e32 v117, 0x4b800000, v116
	v_cmp_gt_f32_e32 vcc, s49, v116
	s_nop 1
	v_cndmask_b32_e32 v116, v116, v117, vcc
	v_rsq_f32_e32 v116, v116
	s_nop 0
	v_mul_f32_e32 v117, 0x45800000, v116
	v_cndmask_b32_e32 v118, v116, v117, vcc
	v_pk_fma_f32 v[110:111], v[110:111], v[118:119], v[70:71] op_sel_hi:[1,0,1]
	v_pk_fma_f32 v[108:109], v[108:109], v[118:119], v[68:69] op_sel_hi:[1,0,1]
	v_pk_fma_f32 v[106:107], v[106:107], v[118:119], v[66:67] op_sel_hi:[1,0,1]
	v_pk_fma_f32 v[104:105], v[104:105], v[118:119], v[64:65] op_sel_hi:[1,0,1]
	s_cbranch_scc1 .LBB0_829
	s_mov_b64 s[34:35], 0
	s_cmp_eq_u32 s80, 1
	s_mov_b64 s[20:21], 0
	s_cbranch_scc0 .LBB0_830
	v_mov_b32_e32 v120, v109
	v_mov_b32_e32 v121, v105
	v_mov_b32_e32 v116, v108
	v_mov_b32_e32 v117, v104
	v_pk_mul_f32 v[120:121], v[120:121], v[120:121]
	v_mov_b32_e32 v122, v111
	v_mov_b32_e32 v123, v107
	v_pk_fma_f32 v[116:117], v[116:117], v[116:117], v[120:121]
	v_mov_b32_e32 v120, v110
	v_mov_b32_e32 v121, v106
	v_pk_mul_f32 v[122:123], v[122:123], v[122:123]
	s_and_b64 s[20:21], s[4:5], exec
	v_pk_fma_f32 v[120:121], v[120:121], v[120:121], v[122:123]
	s_nop 0
	v_pk_add_f32 v[116:117], v[116:117], v[120:121]
	s_nop 0
	v_add_f32_e32 v116, v116, v117
	ds_bpermute_b32 v117, v172, v116
	s_waitcnt lgkmcnt(0)
	v_add_f32_e32 v120, v116, v117
	ds_bpermute_b32 v121, v173, v120
	s_branch .LBB0_830

; __device__ __forceinline__ float sum4(f32x4 v) { return (v.x + v.y) + (v.z + v.w); }
; __device__ __forceinline__ float quad_sum(float t, int lane) { t += shx(t, 16, lane); t += shx(t, 32, lane); return t; }
;     template <int A0, int A1> __device__ __forceinline__ void run(const f32x4 (&acc)[2][2][4][2], const Unit& u, int wr, int wc, int fr, int fq) const {
;     ...
;             for (int m = 0; m < 4; ++m) {
;                 const int row = row0 + ai * 128 + m * 16;
;                 const float t = quad_sum(sum4(*(const f32x4*)(ssqp + (size_t)row * 16 + 4 * fq)), fq * 16 + fr);
;                 const float rr = rsqrtf(t * (1.0f / 1024.0f) + EPS);
;                 f32x4 v[2][2];
; #pragma unroll
;                 for (int bj = 0; bj < 2; ++bj)
; #pragma unroll
;                     for (int n = 0; n < 2; ++n) v[bj][n] = acc[ai][bj][m][n] * rr + b[bj][n];
.LBB0_841:
	s_nop 1
	v_or_b32_e32 v98, 48, v162
	v_ashrrev_i32_e32 v99, 31, v98
	v_lshlrev_b64 v[96:97], 6, v[98:99]
	v_lshl_add_u64 v[100:101], v[152:153], 0, v[96:97]
	s_nop 1
	v_mov_b64_e32 v[100:101], v[192:193]
	v_mov_b64_e32 v[102:103], v[194:195]
	s_cmp_lt_i32 s80, 1
	s_waitcnt vmcnt(0)
	v_mov_b32_e32 v104, v101
	v_mov_b32_e32 v105, v102
	v_mov_b32_e32 v101, v103
	v_pk_add_f32 v[100:101], v[104:105], v[100:101]
	s_nop 0
	v_add_f32_e32 v100, v100, v101
	ds_bpermute_b32 v101, v172, v100
	s_waitcnt lgkmcnt(0)
	v_add_f32_e32 v100, v100, v101
	ds_bpermute_b32 v101, v173, v100
	s_waitcnt lgkmcnt(0)
	v_add_f32_e32 v100, v100, v101
	v_fmamk_f32 v100, v100, 0x3a800000, v252
	v_mul_f32_e32 v101, 0x4b800000, v100
	v_cmp_gt_f32_e32 vcc, s49, v100
	s_nop 1
	v_cndmask_b32_e32 v100, v100, v101, vcc
	v_rsq_f32_e32 v100, v100
	s_nop 0
	v_mul_f32_e32 v101, 0x45800000, v100
	v_cndmask_b32_e32 v102, v100, v101, vcc
	v_pk_fma_f32 v[94:95], v[94:95], v[102:103], v[70:71] op_sel_hi:[1,0,1]
	v_pk_fma_f32 v[92:93], v[92:93], v[102:103], v[68:69] op_sel_hi:[1,0,1]
	v_pk_fma_f32 v[90:91], v[90:91], v[102:103], v[66:67] op_sel_hi:[1,0,1]
	v_pk_fma_f32 v[88:89], v[88:89], v[102:103], v[64:65] op_sel_hi:[1,0,1]
	s_cbranch_scc1 .LBB0_844
	s_mov_b64 s[34:35], 0
	s_cmp_eq_u32 s80, 1
	s_mov_b64 s[20:21], 0
	s_cbranch_scc0 .LBB0_845
	v_mov_b32_e32 v104, v93
	v_mov_b32_e32 v105, v89
	v_mov_b32_e32 v100, v92
	v_mov_b32_e32 v101, v88
	v_pk_mul_f32 v[104:105], v[104:105], v[104:105]
	v_mov_b32_e32 v106, v95
	v_mov_b32_e32 v107, v91
	v_pk_fma_f32 v[100:101], v[100:101], v[100:101], v[104:105]
	v_mov_b32_e32 v104, v94
	v_mov_b32_e32 v105, v90
	v_pk_mul_f32 v[106:107], v[106:107], v[106:107]
	s_and_b64 s[20:21], s[4:5], exec
	v_pk_fma_f32 v[104:105], v[104:105], v[104:105], v[106:107]
	s_nop 0
	v_pk_add_f32 v[100:101], v[100:101], v[104:105]
	s_nop 0
	v_add_f32_e32 v100, v100, v101
	ds_bpermute_b32 v101, v172, v100
	s_waitcnt lgkmcnt(0)
	v_add_f32_e32 v104, v100, v101
	ds_bpermute_b32 v105, v173, v104
	s_branch .LBB0_845

; __device__ __forceinline__ float sum4(f32x4 v) { return (v.x + v.y) + (v.z + v.w); }
; __device__ __forceinline__ float quad_sum(float t, int lane) { t += shx(t, 16, lane); t += shx(t, 32, lane); return t; }
;     template <int A0, int A1> __device__ __forceinline__ void run(const f32x4 (&acc)[2][2][4][2], const Unit& u, int wr, int wc, int fr, int fq) const {
;     ...
;             for (int m = 0; m < 4; ++m) {
;                 const int row = row0 + ai * 128 + m * 16;
;                 const float t = quad_sum(sum4(*(const f32x4*)(ssqp + (size_t)row * 16 + 4 * fq)), fq * 16 + fr);
;                 const float rr = rsqrtf(t * (1.0f / 1024.0f) + EPS);
;                 f32x4 v[2][2];
; #pragma unroll
;                 for (int bj = 0; bj < 2; ++bj)
; #pragma unroll
;                     for (int n = 0; n < 2; ++n) v[bj][n] = acc[ai][bj][m][n] * rr + b[bj][n];
.LBB0_856:
	s_nop 1
	v_add_u32_e32 v82, 0x80, v162
	v_ashrrev_i32_e32 v83, 31, v82
	v_lshlrev_b64 v[80:81], 6, v[82:83]
	v_lshl_add_u64 v[84:85], v[152:153], 0, v[80:81]
	s_nop 1
	v_mov_b64_e32 v[84:85], v[196:197]
	v_mov_b64_e32 v[86:87], v[198:199]
	s_cmp_lt_i32 s80, 1
	s_waitcnt vmcnt(0)
	v_mov_b32_e32 v88, v85
	v_mov_b32_e32 v89, v86
	v_mov_b32_e32 v85, v87
	v_pk_add_f32 v[84:85], v[88:89], v[84:85]
	s_nop 0
	v_add_f32_e32 v84, v84, v85
	ds_bpermute_b32 v85, v172, v84
	s_waitcnt lgkmcnt(0)
	v_add_f32_e32 v84, v84, v85
	ds_bpermute_b32 v85, v173, v84
	s_waitcnt lgkmcnt(0)
	v_add_f32_e32 v84, v84, v85
	v_fmamk_f32 v84, v84, 0x3a800000, v252
	v_mul_f32_e32 v85, 0x4b800000, v84
	v_cmp_gt_f32_e32 vcc, s49, v84
	s_nop 1
	v_cndmask_b32_e32 v84, v84, v85, vcc
	v_rsq_f32_e32 v84, v84
	s_nop 0
	v_mul_f32_e32 v85, 0x45800000, v84
	v_cndmask_b32_e32 v86, v84, v85, vcc
	v_pk_fma_f32 v[78:79], v[78:79], v[86:87], v[70:71] op_sel_hi:[1,0,1]
	v_pk_fma_f32 v[76:77], v[76:77], v[86:87], v[68:69] op_sel_hi:[1,0,1]
	v_pk_fma_f32 v[74:75], v[74:75], v[86:87], v[66:67] op_sel_hi:[1,0,1]
	v_pk_fma_f32 v[72:73], v[72:73], v[86:87], v[64:65] op_sel_hi:[1,0,1]
	s_cbranch_scc1 .LBB0_859
	s_mov_b64 s[34:35], 0
	s_cmp_eq_u32 s80, 1
	s_mov_b64 s[20:21], 0
	s_cbranch_scc0 .LBB0_860
	v_mov_b32_e32 v88, v77
	v_mov_b32_e32 v89, v73
	v_mov_b32_e32 v84, v76
	v_mov_b32_e32 v85, v72
	v_pk_mul_f32 v[88:89], v[88:89], v[88:89]
	v_mov_b32_e32 v90, v79
	v_mov_b32_e32 v91, v75
	v_pk_fma_f32 v[84:85], v[84:85], v[84:85], v[88:89]
	v_mov_b32_e32 v88, v78
	v_mov_b32_e32 v89, v74
	v_pk_mul_f32 v[90:91], v[90:91], v[90:91]
	s_and_b64 s[20:21], s[4:5], exec
	v_pk_fma_f32 v[88:89], v[88:89], v[88:89], v[90:91]
	s_nop 0
	v_pk_add_f32 v[84:85], v[84:85], v[88:89]
	s_nop 0
	v_add_f32_e32 v84, v84, v85
	ds_bpermute_b32 v85, v172, v84
	s_waitcnt lgkmcnt(0)
	v_add_f32_e32 v88, v84, v85
	ds_bpermute_b32 v89, v173, v88
	s_branch .LBB0_860

; __device__ __forceinline__ float sum4(f32x4 v) { return (v.x + v.y) + (v.z + v.w); }
; __device__ __forceinline__ float quad_sum(float t, int lane) { t += shx(t, 16, lane); t += shx(t, 32, lane); return t; }
;     template <int A0, int A1> __device__ __forceinline__ void run(const f32x4 (&acc)[2][2][4][2], const Unit& u, int wr, int wc, int fr, int fq) const {
;     ...
;             for (int m = 0; m < 4; ++m) {
;                 const int row = row0 + ai * 128 + m * 16;
;                 const float t = quad_sum(sum4(*(const f32x4*)(ssqp + (size_t)row * 16 + 4 * fq)), fq * 16 + fr);
;                 const float rr = rsqrtf(t * (1.0f / 1024.0f) + EPS);
;                 f32x4 v[2][2];
; #pragma unroll
;                 for (int bj = 0; bj < 2; ++bj)
; #pragma unroll
;                     for (int n = 0; n < 2; ++n) v[bj][n] = acc[ai][bj][m][n] * rr + b[bj][n];
.LBB0_871:
	s_nop 1
	v_add_u32_e32 v58, 0x90, v162
	v_ashrrev_i32_e32 v59, 31, v58
	v_lshlrev_b64 v[56:57], 6, v[58:59]
	v_lshl_add_u64 v[60:61], v[152:153], 0, v[56:57]
	s_nop 1
	v_mov_b64_e32 v[60:61], v[200:201]
	v_mov_b64_e32 v[62:63], v[202:203]
	s_cmp_lt_i32 s80, 1
	s_waitcnt vmcnt(0)
	v_mov_b32_e32 v72, v61
	v_mov_b32_e32 v73, v62
	v_mov_b32_e32 v61, v63
	v_pk_add_f32 v[60:61], v[72:73], v[60:61]
	s_nop 0
	v_add_f32_e32 v60, v60, v61
	ds_bpermute_b32 v61, v172, v60
	s_waitcnt lgkmcnt(0)
	v_add_f32_e32 v60, v60, v61
	ds_bpermute_b32 v61, v173, v60
	s_waitcnt lgkmcnt(0)
	v_add_f32_e32 v60, v60, v61
	v_fmamk_f32 v60, v60, 0x3a800000, v252
	v_mul_f32_e32 v61, 0x4b800000, v60
	v_cmp_gt_f32_e32 vcc, s49, v60
	s_nop 1
	v_cndmask_b32_e32 v60, v60, v61, vcc
	v_rsq_f32_e32 v60, v60
	s_nop 0
	v_mul_f32_e32 v61, 0x45800000, v60
	v_cndmask_b32_e32 v62, v60, v61, vcc
	v_pk_fma_f32 v[46:47], v[46:47], v[62:63], v[70:71] op_sel_hi:[1,0,1]
	v_pk_fma_f32 v[44:45], v[44:45], v[62:63], v[68:69] op_sel_hi:[1,0,1]
	v_pk_fma_f32 v[42:43], v[42:43], v[62:63], v[66:67] op_sel_hi:[1,0,1]
	v_pk_fma_f32 v[40:41], v[40:41], v[62:63], v[64:65] op_sel_hi:[1,0,1]
	s_cbranch_scc1 .LBB0_874
	s_mov_b64 s[34:35], 0
	s_cmp_eq_u32 s80, 1
	s_mov_b64 s[20:21], 0
	s_cbranch_scc0 .LBB0_875
	v_mov_b32_e32 v72, v45
	v_mov_b32_e32 v73, v41
	v_mov_b32_e32 v60, v44
	v_mov_b32_e32 v61, v40
	v_pk_mul_f32 v[72:73], v[72:73], v[72:73]
	v_mov_b32_e32 v74, v47
	v_mov_b32_e32 v75, v43
	v_pk_fma_f32 v[60:61], v[60:61], v[60:61], v[72:73]
	v_mov_b32_e32 v72, v46
	v_mov_b32_e32 v73, v42
	v_pk_mul_f32 v[74:75], v[74:75], v[74:75]
	s_and_b64 s[20:21], s[4:5], exec
	v_pk_fma_f32 v[72:73], v[72:73], v[72:73], v[74:75]
	s_nop 0
	v_pk_add_f32 v[60:61], v[60:61], v[72:73]
	s_nop 0
	v_add_f32_e32 v60, v60, v61
	ds_bpermute_b32 v61, v172, v60
	s_waitcnt lgkmcnt(0)
	v_add_f32_e32 v72, v60, v61
	ds_bpermute_b32 v73, v173, v72
	s_branch .LBB0_875

; __device__ __forceinline__ float sum4(f32x4 v) { return (v.x + v.y) + (v.z + v.w); }
; __device__ __forceinline__ float quad_sum(float t, int lane) { t += shx(t, 16, lane); t += shx(t, 32, lane); return t; }
;     template <int A0, int A1> __device__ __forceinline__ void run(const f32x4 (&acc)[2][2][4][2], const Unit& u, int wr, int wc, int fr, int fq) const {
;     ...
;             for (int m = 0; m < 4; ++m) {
;                 const int row = row0 + ai * 128 + m * 16;
;                 const float t = quad_sum(sum4(*(const f32x4*)(ssqp + (size_t)row * 16 + 4 * fq)), fq * 16 + fr);
;                 const float rr = rsqrtf(t * (1.0f / 1024.0f) + EPS);
;                 f32x4 v[2][2];
; #pragma unroll
;                 for (int bj = 0; bj < 2; ++bj)
; #pragma unroll
;                     for (int n = 0; n < 2; ++n) v[bj][n] = acc[ai][bj][m][n] * rr + b[bj][n];
.LBB0_886:
	s_nop 1
	v_add_u32_e32 v34, 0xa0, v162
	v_ashrrev_i32_e32 v35, 31, v34
	v_lshlrev_b64 v[32:33], 6, v[34:35]
	v_lshl_add_u64 v[36:37], v[152:153], 0, v[32:33]
	s_nop 1
	v_mov_b64_e32 v[36:37], v[204:205]
	v_mov_b64_e32 v[38:39], v[206:207]
	s_cmp_lt_i32 s80, 1
	s_waitcnt vmcnt(0)
	v_mov_b32_e32 v40, v37
	v_mov_b32_e32 v41, v38
	v_mov_b32_e32 v37, v39
	v_pk_add_f32 v[36:37], v[40:41], v[36:37]
	s_nop 0
	v_add_f32_e32 v36, v36, v37
	ds_bpermute_b32 v37, v172, v36
	s_waitcnt lgkmcnt(0)
	v_add_f32_e32 v36, v36, v37
	ds_bpermute_b32 v37, v173, v36
	s_waitcnt lgkmcnt(0)
	v_add_f32_e32 v36, v36, v37
	v_fmamk_f32 v36, v36, 0x3a800000, v252
	v_mul_f32_e32 v37, 0x4b800000, v36
	v_cmp_gt_f32_e32 vcc, s49, v36
	s_nop 1
	v_cndmask_b32_e32 v36, v36, v37, vcc
	v_rsq_f32_e32 v36, v36
	s_nop 0
	v_mul_f32_e32 v37, 0x45800000, v36
	v_cndmask_b32_e32 v38, v36, v37, vcc
	v_pk_fma_f32 v[30:31], v[30:31], v[38:39], v[70:71] op_sel_hi:[1,0,1]
	v_pk_fma_f32 v[28:29], v[28:29], v[38:39], v[68:69] op_sel_hi:[1,0,1]
	v_pk_fma_f32 v[26:27], v[26:27], v[38:39], v[66:67] op_sel_hi:[1,0,1]
	v_pk_fma_f32 v[24:25], v[24:25], v[38:39], v[64:65] op_sel_hi:[1,0,1]
	s_cbranch_scc1 .LBB0_889
	s_mov_b64 s[34:35], 0
	s_cmp_eq_u32 s80, 1
	s_mov_b64 s[20:21], 0
	s_cbranch_scc0 .LBB0_890
	v_mov_b32_e32 v40, v29
	v_mov_b32_e32 v41, v25
	v_mov_b32_e32 v36, v28
	v_mov_b32_e32 v37, v24
	v_pk_mul_f32 v[40:41], v[40:41], v[40:41]
	v_mov_b32_e32 v42, v31
	v_mov_b32_e32 v43, v27
	v_pk_fma_f32 v[36:37], v[36:37], v[36:37], v[40:41]
	v_mov_b32_e32 v40, v30
	v_mov_b32_e32 v41, v26
	v_pk_mul_f32 v[42:43], v[42:43], v[42:43]
	s_and_b64 s[20:21], s[4:5], exec
	v_pk_fma_f32 v[40:41], v[40:41], v[40:41], v[42:43]
	s_nop 0
	v_pk_add_f32 v[36:37], v[36:37], v[40:41]
	s_nop 0
	v_add_f32_e32 v36, v36, v37
	ds_bpermute_b32 v37, v172, v36
	s_waitcnt lgkmcnt(0)
	v_add_f32_e32 v40, v36, v37
	ds_bpermute_b32 v41, v173, v40
	s_branch .LBB0_890

; __device__ __forceinline__ float sum4(f32x4 v) { return (v.x + v.y) + (v.z + v.w); }
; __device__ __forceinline__ float quad_sum(float t, int lane) { t += shx(t, 16, lane); t += shx(t, 32, lane); return t; }
;     template <int A0, int A1> __device__ __forceinline__ void run(const f32x4 (&acc)[2][2][4][2], const Unit& u, int wr, int wc, int fr, int fq) const {
;     ...
;             for (int m = 0; m < 4; ++m) {
;                 const int row = row0 + ai * 128 + m * 16;
;                 const float t = quad_sum(sum4(*(const f32x4*)(ssqp + (size_t)row * 16 + 4 * fq)), fq * 16 + fr);
;                 const float rr = rsqrtf(t * (1.0f / 1024.0f) + EPS);
;                 f32x4 v[2][2];
; #pragma unroll
;                 for (int bj = 0; bj < 2; ++bj)
; #pragma unroll
;                     for (int n = 0; n < 2; ++n) v[bj][n] = acc[ai][bj][m][n] * rr + b[bj][n];
.LBB0_901:
	s_nop 1
	v_add_u32_e32 v18, 0xb0, v162
	v_ashrrev_i32_e32 v19, 31, v18
	v_lshlrev_b64 v[16:17], 6, v[18:19]
	v_lshl_add_u64 v[20:21], v[152:153], 0, v[16:17]
	s_nop 1
	v_mov_b64_e32 v[20:21], v[208:209]
	v_mov_b64_e32 v[22:23], v[210:211]
	s_cmp_lt_i32 s80, 1
	s_waitcnt vmcnt(0)
	v_mov_b32_e32 v24, v21
	v_mov_b32_e32 v25, v22
	v_mov_b32_e32 v21, v23
	v_pk_add_f32 v[20:21], v[24:25], v[20:21]
	s_nop 0
	v_add_f32_e32 v20, v20, v21
	ds_bpermute_b32 v21, v172, v20
	s_waitcnt lgkmcnt(0)
	v_add_f32_e32 v20, v20, v21
	ds_bpermute_b32 v21, v173, v20
	s_waitcnt lgkmcnt(0)
	v_add_f32_e32 v20, v20, v21
	v_fmamk_f32 v20, v20, 0x3a800000, v252
	v_mul_f32_e32 v21, 0x4b800000, v20
	v_cmp_gt_f32_e32 vcc, s49, v20
	s_nop 1
	v_cndmask_b32_e32 v20, v20, v21, vcc
	v_rsq_f32_e32 v20, v20
	s_nop 0
	v_mul_f32_e32 v21, 0x45800000, v20
	v_cndmask_b32_e32 v22, v20, v21, vcc
	v_pk_fma_f32 v[14:15], v[14:15], v[22:23], v[70:71] op_sel_hi:[1,0,1]
	v_pk_fma_f32 v[12:13], v[12:13], v[22:23], v[68:69] op_sel_hi:[1,0,1]
	v_pk_fma_f32 v[10:11], v[10:11], v[22:23], v[66:67] op_sel_hi:[1,0,1]
	v_pk_fma_f32 v[8:9], v[8:9], v[22:23], v[64:65] op_sel_hi:[1,0,1]
	s_cbranch_scc1 .LBB0_904
	s_mov_b64 s[34:35], 0
	s_cmp_eq_u32 s80, 1
	s_mov_b64 s[20:21], 0
	s_cbranch_scc0 .LBB0_905
	v_mov_b32_e32 v24, v13
	v_mov_b32_e32 v25, v9
	v_mov_b32_e32 v20, v12
	v_mov_b32_e32 v21, v8
	v_pk_mul_f32 v[24:25], v[24:25], v[24:25]
	v_mov_b32_e32 v26, v15
	v_mov_b32_e32 v27, v11
	v_pk_fma_f32 v[20:21], v[20:21], v[20:21], v[24:25]
	v_mov_b32_e32 v24, v14
	v_mov_b32_e32 v25, v10
	v_pk_mul_f32 v[26:27], v[26:27], v[26:27]
	s_and_b64 s[20:21], s[4:5], exec
	v_pk_fma_f32 v[24:25], v[24:25], v[24:25], v[26:27]
	s_nop 0
	v_pk_add_f32 v[20:21], v[20:21], v[24:25]
	s_nop 0
	v_add_f32_e32 v20, v20, v21
	ds_bpermute_b32 v21, v172, v20
	s_waitcnt lgkmcnt(0)
	v_add_f32_e32 v24, v20, v21
	ds_bpermute_b32 v25, v173, v24
	s_branch .LBB0_905

; __global__ void __launch_bounds__(512, 2) mega_fwd(Args a_byval) {
;     ...
;         { const bool ffn_in_seam = (ph >= 2 && ph < 18 && (((ph - 2) & 7) == 0 || ((ph - 2) & 7) == 6)) && (int)gridDim.x == 256;
;           if (it + 1 < it_hi && !ffn_in_seam) grid.sync(); }
.LBB0_1498:
	v_readlane_b32 s2, v255, 8
	v_readlane_b32 s3, v255, 9
	s_waitcnt vmcnt(0) lgkmcnt(0)
	s_barrier
	s_and_saveexec_b64 s[4:5], s[2:3]
	s_cbranch_execnz .LBB0_1499
	s_getpc_b64 s[98:99]

; __global__ void __launch_bounds__(512, 2) mega_fwd(Args a_byval) {
;     ...
;         { const bool ffn_in_seam = (ph >= 2 && ph < 18 && (((ph - 2) & 7) == 0 || ((ph - 2) & 7) == 6)) && (int)gridDim.x == 256;
;           if (it + 1 < it_hi && !ffn_in_seam) grid.sync(); }
.LBB0_1499:
	buffer_wbl2 sc1
	v_readlane_b32 s6, v255, 12
	v_readlane_b32 s7, v255, 13
	s_waitcnt vmcnt(0)
	s_load_dwordx2 s[6:7], s[6:7], 0xa0
	v_readlane_b32 s0, v255, 14
	s_nop 0
	s_add_i32 s101, s101, s0
	v_mov_b32_e32 v0, 1
	s_waitcnt lgkmcnt(0)
	s_add_u32 s6, s6, 0x3a000
	s_addc_u32 s7, s7, 0
	global_atomic_add v129, v0, s[6:7]
.Lgb_spin:
	s_sleep 1
	global_load_dword v1, v129, s[6:7] sc1
	s_waitcnt vmcnt(0)
	v_cmp_gt_u32_e32 vcc, s101, v1
	s_cbranch_vccnz .Lgb_spin
	s_getpc_b64 s[98:99]

; __global__ void __launch_bounds__(512, 2) mega_fwd(Args a_byval) {
;     extern __shared__ __attribute__((aligned(16))) unsigned char lds_raw[];
	.amdhsa_kernel _Z8mega_fwd4Args
		.amdhsa_group_segment_fixed_size 0
		.amdhsa_private_segment_fixed_size 0
		.amdhsa_kernarg_size 432
		.amdhsa_user_sgpr_count 2
		.amdhsa_user_sgpr_dispatch_ptr 0
		.amdhsa_user_sgpr_queue_ptr 0
		.amdhsa_user_sgpr_kernarg_segment_ptr 1
		.amdhsa_user_sgpr_dispatch_id 0
		.amdhsa_user_sgpr_kernarg_preload_length 0
		.amdhsa_user_sgpr_kernarg_preload_offset 0
		.amdhsa_user_sgpr_private_segment_size 0
		.amdhsa_uses_dynamic_stack 0
		.amdhsa_enable_private_segment 0
		.amdhsa_system_sgpr_workgroup_id_x 1
		.amdhsa_system_sgpr_workgroup_id_y 0
		.amdhsa_system_sgpr_workgroup_id_z 0
		.amdhsa_system_sgpr_workgroup_info 0
		.amdhsa_system_vgpr_workitem_id 2
		.amdhsa_next_free_vgpr 256
		.amdhsa_next_free_sgpr 102
		.amdhsa_accum_offset 256
		.amdhsa_reserve_vcc 1
		.amdhsa_float_round_mode_32 0
		.amdhsa_float_round_mode_16_64 0
		.amdhsa_float_denorm_mode_32 3
		.amdhsa_float_denorm_mode_16_64 3
		.amdhsa_dx10_clamp 1
		.amdhsa_ieee_mode 1
		.amdhsa_fp16_overflow 0
		.amdhsa_tg_split 0
		.amdhsa_exception_fp_ieee_invalid_op 0
		.amdhsa_exception_fp_denorm_src 0
		.amdhsa_exception_fp_ieee_div_zero 0
		.amdhsa_exception_fp_ieee_overflow 0
		.amdhsa_exception_fp_ieee_underflow 0
		.amdhsa_exception_fp_ieee_inexact 0
		.amdhsa_exception_int_div_zero 0
	.end_amdhsa_kernel

; __global__ void __launch_bounds__(512, 2) mega_fwd(Args a_byval) {
amdhsa.kernels:
  - .agpr_count:     0
    .args:
      - .offset:         0
        .size:           176
        .value_kind:     by_value
      - .offset:         176
        .size:           4
        .value_kind:     hidden_block_count_x
      - .offset:         180
        .size:           4
        .value_kind:     hidden_block_count_y
      - .offset:         184
        .size:           4
        .value_kind:     hidden_block_count_z
      - .offset:         188
        .size:           2
        .value_kind:     hidden_group_size_x
      - .offset:         190
        .size:           2
        .value_kind:     hidden_group_size_y
      - .offset:         192
        .size:           2
        .value_kind:     hidden_group_size_z
      - .offset:         194
        .size:           2
        .value_kind:     hidden_remainder_x
      - .offset:         196
        .size:           2
        .value_kind:     hidden_remainder_y
      - .offset:         198
        .size:           2
        .value_kind:     hidden_remainder_z
      - .offset:         216
        .size:           8
        .value_kind:     hidden_global_offset_x
      - .offset:         224
        .size:           8
        .value_kind:     hidden_global_offset_y
      - .offset:         232
        .size:           8
        .value_kind:     hidden_global_offset_z
      - .offset:         240
        .size:           2
        .value_kind:     hidden_grid_dims
      - .offset:         264
        .size:           8
        .value_kind:     hidden_multigrid_sync_arg
      - .offset:         296
        .size:           4
        .value_kind:     hidden_dynamic_lds_size
    .group_segment_fixed_size: 0
    .kernarg_segment_align: 8
    .kernarg_segment_size: 432
    .language:       OpenCL C
    .language_version:
      - 2
      - 0
    .max_flat_workgroup_size: 512
    .name:           _Z8mega_fwd4Args
    .private_segment_fixed_size: 0
    .sgpr_count:     108
    .sgpr_spill_count: 59
    .symbol:         _Z8mega_fwd4Args.kd
    .uniform_work_group_size: 1
    .uses_dynamic_stack: false
    .vgpr_count:     256
    .vgpr_spill_count: 0
    .wavefront_size: 64
